# P4c prologue de-serialised: earlier-group state loads of all groups issued up front (loop unrolled by hand), (m,decay) load issued with the first load
# speedup vs baseline: 1.0032x; 1.0032x over previous
; template <bool STATE_ONLY>
; __device__ __forceinline__ void mlstm_group(const Args& a, LAS unsigned char* lds, int bh, int grp, int tid, int wave, int lane) {
;     ...
;     const float b_i = a.bi[h], b_f = a.bf[h];
;     const int c0 = grp * ML_GROUP;
;     f32x4 cacc[4];
; #pragma unroll
;     for (int kt = 0; kt < 4; ++kt) cacc[kt] = (f32x4){0.f, 0.f, 0.f, 0.f};
;     float m_prev, bsum = 0.f;
;     if constexpr (STATE_ONLY) {
;         m_prev = -1e30f;
;         if (tid < 64) s_n[(c0 & 1) * 64 + tid] = 0.f;
;     } else {
;         float m = 0.f;
;         for (int c = 0; c < c0; ++c) { const float bl_c = CHS[(bh * 32 + c) * 2], am_c = CHS[(bh * 32 + c) * 2 + 1]; m = fmaxf(bl_c + m, am_c); }
;         m_prev = m;
;         float nacc = 0.f;
;         for (int gp = 0; gp < grp; ++gp) {
;             float e = SG[(bh * 4 + gp) * 2] - m;
;             for (int g2 = gp + 1; g2 < grp; ++g2) e += SG[(bh * 4 + g2) * 2 + 1];
.LBB0_1222:
	s_andn2_b64 vcc, exec, s[2:3]
	s_cbranch_vccnz .LBB0_1254
	s_bfe_u32 s5, s81, 0x20002
	s_lshl_b32 s4, s5, 2
	v_mov_b32_e32 v0, s4
	global_load_dword v32, v0, s[56:57]
	global_load_dword v15, v0, s[58:59]
	s_ashr_i32 s1, s81, 2
	s_lshl_b32 s0, s92, 3
	s_and_b32 s12, s1, -4
	s_add_i32 s12, s12, s0
	s_and_b32 s1, s81, 3
	s_or_b32 s8, s12, s5
	s_lshl_b32 s0, s1, 3
	s_cmp_lg_u32 s1, 0
	s_cselect_b64 s[2:3], -1, 0
	s_cmp_eq_u32 s1, 0
	s_cbranch_scc1 .LBB0_1226
	s_lshl_b32 s6, s8, 6
	s_ashr_i32 s7, s6, 31
	s_lshl_b64 s[6:7], s[6:7], 2
	s_add_u32 s6, s74, s6
	s_addc_u32 s7, s75, s7
	s_add_u32 s6, s6, 0x1e010800
	s_addc_u32 s7, s7, 0
	v_and_b32_e32 v0, 31, v152
	v_lshlrev_b32_e32 v0, 3, v0
	global_load_dwordx2 v[64:65], v0, s[6:7]
	s_mov_b32 s9, s0
	v_mov_b32_e32 v154, 0
	s_mov_b32 s24, 0
	s_add_u32 s28, s74, 0x1e010000
	s_addc_u32 s29, s75, 0
	s_lshl_b32 s27, s8, 5
	v_and_b32_e32 v68, 3, v152
	v_lshlrev_b32_e32 v68, 3, v68
	v_add_u32_e32 v68, s27, v68
	global_load_dwordx2 v[66:67], v68, s[28:29]
	s_waitcnt vmcnt(0)

; template <bool STATE_ONLY>
; __device__ __forceinline__ void mlstm_group(const Args& a, LAS unsigned char* lds, int bh, int grp, int tid, int wave, int lane) {
;     ...
;         for (int gp = 0; gp < grp; ++gp) {
;             float e = SG[(bh * 4 + gp) * 2] - m;
;             for (int g2 = gp + 1; g2 < grp; ++g2) e += SG[(bh * 4 + g2) * 2 + 1];
;             const float coef = __expf(e);
;             const float* cg = CG + (size_t)(bh * 4 + gp) * 8192;
; #pragma unroll
;             for (int kt = 0; kt < 4; ++kt)
; #pragma unroll
;                 for (int i = 0; i < 4; ++i) cacc[kt][i] += coef * cg[(16 * wave + 4 * fq + i) * 64 + 16 * kt + fr];
;             if (tid < 64) nacc += coef * NGs[(bh * 4 + gp) * 64 + tid];
.LBB0_1227:
	v_and_b32_e32 v63, 15, v153
	v_lshrrev_b32_e32 v62, 4, v152
	s_andn2_b64 vcc, exec, s[2:3]
	v_cmp_gt_u32_e64 s[2:3], 64, v153
	v_or_b32_e32 v72, 48, v152
	s_cbranch_vccnz .LBB0_1234
	s_add_u32 s13, s74, 0x1d800000
	s_addc_u32 s14, s75, 0
	s_add_u32 s15, s74, 0x1e010000
	s_addc_u32 s16, s75, 0
	s_add_u32 s6, s74, 0x1e000000
	v_lshlrev_b32_e32 v0, 8, v62
	s_addc_u32 s7, s75, 0
	s_lshl_b32 s17, s8, 2
	v_and_b32_e32 v68, 3, v152
	v_lshlrev_b32_e32 v68, 3, v68
	s_lshl_b32 s27, s17, 3
	v_add_u32_e32 v68, s27, v68
	s_mov_b32 s28, s15
	s_mov_b32 s29, s16
	v_lshl_or_b32 v2, s78, 10, v0
	s_add_i32 s8, s12, s5
	v_or_b32_e32 v0, v2, v63
	v_ashrrev_i32_e32 v3, 31, v2
	v_or_b32_e32 v4, v2, v72
	s_lshl_b32 s8, s8, 3
	v_mov_b32_e32 v31, 0
	v_ashrrev_i32_e32 v1, 31, v0
	v_ashrrev_i32_e32 v5, 31, v4
	v_mov_b32_e32 v2, v0
	v_or_b32_e32 v6, 16, v0
	v_mov_b32_e32 v7, v3
	v_or_b32_e32 v8, 32, v0
	v_mov_b32_e32 v9, v3
	v_mov_b32_e32 v10, v4
	v_mov_b32_e32 v11, v3
	s_add_i32 s18, s1, -1
	s_or_b32 s19, s8, 2
	s_mov_b32 s20, 0
	v_mov_b32_e32 v30, 0
	v_mov_b32_e32 v42, 0
	v_mov_b32_e32 v43, v31
	v_mov_b32_e32 v52, 0
	v_mov_b32_e32 v53, v31
	v_mov_b32_e32 v54, 0
	v_mov_b32_e32 v55, v31
	v_mov_b32_e32 v44, 0
	v_mov_b32_e32 v45, v31
	v_mov_b32_e32 v46, 0
	v_mov_b32_e32 v47, v31
	v_mov_b32_e32 v48, 0
	v_mov_b32_e32 v49, v31
	v_mov_b32_e32 v50, 0
	v_mov_b32_e32 v51, v31
	v_mov_b32_e32 v40, 0
	v_mov_b32_e32 v41, v31
	s_waitcnt vmcnt(0)
	s_branch .LBB0_1230
.LBB0_1230:
	s_cmp_le_u32 s1, 0
	s_cbranch_scc1 .Lcmb_issued
	v_readlane_b32 s25, v66, 0
	s_nop 1
	v_sub_f32_e32 v96, s25, v154
	s_cmp_le_u32 s1, 1
	s_cbranch_scc1 .Lcmb_w0
	v_readlane_b32 s26, v67, 1
	s_nop 1
	v_add_f32_e32 v96, s26, v96
	s_cmp_le_u32 s1, 2
	s_cbranch_scc1 .Lcmb_w0
	v_readlane_b32 s26, v67, 2
	s_nop 1
	v_add_f32_e32 v96, s26, v96
.Lcmb_w0:
	v_mul_f32_e32 v96, 0x3fb8aa3b, v96
	v_exp_f32_e32 v96, v96
	s_add_i32 s8, s17, 0
	s_ashr_i32 s9, s8, 31
	s_lshl_b64 s[10:11], s[8:9], 15
	s_add_u32 s10, s13, s10
	s_addc_u32 s11, s14, s11
	v_lshl_add_u64 v[140:141], v[0:1], 2, s[10:11]
	v_lshl_add_u64 v[142:143], v[2:3], 2, s[10:11]
	v_lshl_add_u64 v[144:145], v[6:7], 2, s[10:11]
	v_lshl_add_u64 v[146:147], v[8:9], 2, s[10:11]
	v_lshl_add_u64 v[148:149], v[4:5], 2, s[10:11]
	v_lshl_add_u64 v[150:151], v[10:11], 2, s[10:11]
	global_load_dword v80, v[140:141], off
	global_load_dword v81, v[142:143], off offset:256
	global_load_dword v82, v[142:143], off offset:512
	global_load_dword v83, v[142:143], off offset:768
	global_load_dword v84, v[142:143], off offset:64
	global_load_dword v85, v[144:145], off offset:256
	global_load_dword v86, v[144:145], off offset:512
	global_load_dword v87, v[144:145], off offset:768
	global_load_dword v88, v[142:143], off offset:128
	global_load_dword v89, v[146:147], off offset:256
	global_load_dword v90, v[146:147], off offset:512
	global_load_dword v91, v[146:147], off offset:768
	global_load_dword v92, v[148:149], off
	global_load_dword v93, v[150:151], off offset:256
	global_load_dword v94, v[150:151], off offset:512
	global_load_dword v95, v[150:151], off offset:768
	s_and_saveexec_b64 s[22:23], s[2:3]
	s_cbranch_execz .Lcmb_n0
	v_lshl_or_b32 v138, s8, 6, v153
	v_ashrrev_i32_e32 v139, 31, v138
	v_lshl_add_u64 v[138:139], v[138:139], 2, s[6:7]
	global_load_dword v97, v[138:139], off
.Lcmb_n0:
	s_or_b64 exec, exec, s[22:23]
	s_cmp_le_u32 s1, 1
	s_cbranch_scc1 .Lcmb_issued
	v_readlane_b32 s25, v66, 1
	s_nop 1
	v_sub_f32_e32 v116, s25, v154
	s_cmp_le_u32 s1, 2
	s_cbranch_scc1 .Lcmb_w1
	v_readlane_b32 s26, v67, 2
	s_nop 1
	v_add_f32_e32 v116, s26, v116
.Lcmb_w1:
	v_mul_f32_e32 v116, 0x3fb8aa3b, v116
	v_exp_f32_e32 v116, v116
	s_add_i32 s8, s17, 1
	s_ashr_i32 s9, s8, 31
	s_lshl_b64 s[10:11], s[8:9], 15
	s_add_u32 s10, s13, s10
	s_addc_u32 s11, s14, s11
	v_lshl_add_u64 v[140:141], v[0:1], 2, s[10:11]
	v_lshl_add_u64 v[142:143], v[2:3], 2, s[10:11]
	v_lshl_add_u64 v[144:145], v[6:7], 2, s[10:11]
	v_lshl_add_u64 v[146:147], v[8:9], 2, s[10:11]
	v_lshl_add_u64 v[148:149], v[4:5], 2, s[10:11]
	v_lshl_add_u64 v[150:151], v[10:11], 2, s[10:11]
	global_load_dword v100, v[140:141], off
	global_load_dword v101, v[142:143], off offset:256
	global_load_dword v102, v[142:143], off offset:512
	global_load_dword v103, v[142:143], off offset:768
	global_load_dword v104, v[142:143], off offset:64
	global_load_dword v105, v[144:145], off offset:256
	global_load_dword v106, v[144:145], off offset:512
	global_load_dword v107, v[144:145], off offset:768
	global_load_dword v108, v[142:143], off offset:128
	global_load_dword v109, v[146:147], off offset:256
	global_load_dword v110, v[146:147], off offset:512
	global_load_dword v111, v[146:147], off offset:768
	global_load_dword v112, v[148:149], off
	global_load_dword v113, v[150:151], off offset:256
	global_load_dword v114, v[150:151], off offset:512
	global_load_dword v115, v[150:151], off offset:768
	s_and_saveexec_b64 s[22:23], s[2:3]
	s_cbranch_execz .Lcmb_n1
	v_lshl_or_b32 v138, s8, 6, v153
	v_ashrrev_i32_e32 v139, 31, v138
	v_lshl_add_u64 v[138:139], v[138:139], 2, s[6:7]
	global_load_dword v117, v[138:139], off
.Lcmb_n1:
	s_or_b64 exec, exec, s[22:23]
	s_cmp_le_u32 s1, 2
	s_cbranch_scc1 .Lcmb_issued
	v_readlane_b32 s25, v66, 2
	s_nop 1
	v_sub_f32_e32 v136, s25, v154
.Lcmb_w2:
	v_mul_f32_e32 v136, 0x3fb8aa3b, v136
	v_exp_f32_e32 v136, v136
	s_add_i32 s8, s17, 2
	s_ashr_i32 s9, s8, 31
	s_lshl_b64 s[10:11], s[8:9], 15
	s_add_u32 s10, s13, s10
	s_addc_u32 s11, s14, s11
	v_lshl_add_u64 v[140:141], v[0:1], 2, s[10:11]
	v_lshl_add_u64 v[142:143], v[2:3], 2, s[10:11]
	v_lshl_add_u64 v[144:145], v[6:7], 2, s[10:11]
	v_lshl_add_u64 v[146:147], v[8:9], 2, s[10:11]
	v_lshl_add_u64 v[148:149], v[4:5], 2, s[10:11]
	v_lshl_add_u64 v[150:151], v[10:11], 2, s[10:11]
	global_load_dword v120, v[140:141], off
	global_load_dword v121, v[142:143], off offset:256
	global_load_dword v122, v[142:143], off offset:512
	global_load_dword v123, v[142:143], off offset:768
	global_load_dword v124, v[142:143], off offset:64
	global_load_dword v125, v[144:145], off offset:256
	global_load_dword v126, v[144:145], off offset:512
	global_load_dword v127, v[144:145], off offset:768
	global_load_dword v128, v[142:143], off offset:128
	global_load_dword v129, v[146:147], off offset:256
	global_load_dword v130, v[146:147], off offset:512
	global_load_dword v131, v[146:147], off offset:768
	global_load_dword v132, v[148:149], off
	global_load_dword v133, v[150:151], off offset:256
	global_load_dword v134, v[150:151], off offset:512
	global_load_dword v135, v[150:151], off offset:768
	s_and_saveexec_b64 s[22:23], s[2:3]
	s_cbranch_execz .Lcmb_n2
	v_lshl_or_b32 v138, s8, 6, v153
	v_ashrrev_i32_e32 v139, 31, v138
	v_lshl_add_u64 v[138:139], v[138:139], 2, s[6:7]
	global_load_dword v137, v[138:139], off

; template <bool STATE_ONLY>
; __device__ __forceinline__ void mlstm_group(const Args& a, LAS unsigned char* lds, int bh, int grp, int tid, int wave, int lane) {
;     ...
;         for (int gp = 0; gp < grp; ++gp) {
;             float e = SG[(bh * 4 + gp) * 2] - m;
;             for (int g2 = gp + 1; g2 < grp; ++g2) e += SG[(bh * 4 + g2) * 2 + 1];
;             const float coef = __expf(e);
;             const float* cg = CG + (size_t)(bh * 4 + gp) * 8192;
; #pragma unroll
;             for (int kt = 0; kt < 4; ++kt)
; #pragma unroll
;                 for (int i = 0; i < 4; ++i) cacc[kt][i] += coef * cg[(16 * wave + 4 * fq + i) * 64 + 16 * kt + fr];
;             if (tid < 64) nacc += coef * NGs[(bh * 4 + gp) * 64 + tid];
;         }
;         if (tid < 64) s_n[(c0 & 1) * 64 + tid] = nacc;
.Lcmb_issued:
	s_waitcnt vmcnt(0)
	s_cmp_le_u32 s1, 0
	s_cbranch_scc1 .LBB0_1235
	s_and_saveexec_b64 s[22:23], s[2:3]
	v_fmac_f32_e32 v30, v96, v97
	s_or_b64 exec, exec, s[22:23]
	v_mov_b32_e32 v98, v96
	v_pk_fma_f32 v[52:53], v[80:81], v[98:99], v[52:53] op_sel_hi:[1,0,1]
	v_pk_fma_f32 v[54:55], v[98:99], v[82:83], v[54:55] op_sel_hi:[0,1,1]
	v_pk_fma_f32 v[44:45], v[98:99], v[84:85], v[44:45] op_sel_hi:[0,1,1]
	v_pk_fma_f32 v[46:47], v[98:99], v[86:87], v[46:47] op_sel_hi:[0,1,1]
	v_pk_fma_f32 v[48:49], v[98:99], v[88:89], v[48:49] op_sel_hi:[0,1,1]
	v_pk_fma_f32 v[50:51], v[98:99], v[90:91], v[50:51] op_sel_hi:[0,1,1]
	v_pk_fma_f32 v[40:41], v[98:99], v[92:93], v[40:41] op_sel_hi:[0,1,1]
	v_pk_fma_f32 v[42:43], v[98:99], v[94:95], v[42:43] op_sel_hi:[0,1,1]
	s_cmp_le_u32 s1, 1
	s_cbranch_scc1 .LBB0_1235
	s_and_saveexec_b64 s[22:23], s[2:3]
	v_fmac_f32_e32 v30, v116, v117
	s_or_b64 exec, exec, s[22:23]
	v_mov_b32_e32 v118, v116
	v_pk_fma_f32 v[52:53], v[100:101], v[118:119], v[52:53] op_sel_hi:[1,0,1]
	v_pk_fma_f32 v[54:55], v[118:119], v[102:103], v[54:55] op_sel_hi:[0,1,1]
	v_pk_fma_f32 v[44:45], v[118:119], v[104:105], v[44:45] op_sel_hi:[0,1,1]
	v_pk_fma_f32 v[46:47], v[118:119], v[106:107], v[46:47] op_sel_hi:[0,1,1]
	v_pk_fma_f32 v[48:49], v[118:119], v[108:109], v[48:49] op_sel_hi:[0,1,1]
	v_pk_fma_f32 v[50:51], v[118:119], v[110:111], v[50:51] op_sel_hi:[0,1,1]
	v_pk_fma_f32 v[40:41], v[118:119], v[112:113], v[40:41] op_sel_hi:[0,1,1]
	v_pk_fma_f32 v[42:43], v[118:119], v[114:115], v[42:43] op_sel_hi:[0,1,1]
	s_cmp_le_u32 s1, 2
	s_cbranch_scc1 .LBB0_1235
	s_and_saveexec_b64 s[22:23], s[2:3]
	v_fmac_f32_e32 v30, v136, v137
	s_or_b64 exec, exec, s[22:23]
	v_mov_b32_e32 v138, v136
	v_pk_fma_f32 v[52:53], v[120:121], v[138:139], v[52:53] op_sel_hi:[1,0,1]
	v_pk_fma_f32 v[54:55], v[138:139], v[122:123], v[54:55] op_sel_hi:[0,1,1]
	v_pk_fma_f32 v[44:45], v[138:139], v[124:125], v[44:45] op_sel_hi:[0,1,1]
	v_pk_fma_f32 v[46:47], v[138:139], v[126:127], v[46:47] op_sel_hi:[0,1,1]
	v_pk_fma_f32 v[48:49], v[138:139], v[128:129], v[48:49] op_sel_hi:[0,1,1]
	v_pk_fma_f32 v[50:51], v[138:139], v[130:131], v[50:51] op_sel_hi:[0,1,1]
	v_pk_fma_f32 v[40:41], v[138:139], v[132:133], v[40:41] op_sel_hi:[0,1,1]
	v_pk_fma_f32 v[42:43], v[138:139], v[134:135], v[42:43] op_sel_hi:[0,1,1]
	s_branch .LBB0_1235
